# v035topgen
# speedup vs baseline: 1.0032x; 1.0032x over previous
; DEV unsigned xb_ld(unsigned* p) { return __hip_atomic_load(p, __ATOMIC_RELAXED, __HIP_MEMORY_SCOPE_AGENT); }
; DEV unsigned xb_add(unsigned* p, unsigned v) { return __hip_atomic_fetch_add(p, v, __ATOMIC_RELAXED, __HIP_MEMORY_SCOPE_AGENT); }
; #define XB_SPIN(cond, bar) do { unsigned _sp = 0; while (cond) { __builtin_amdgcn_s_sleep(1); \
;     if ((++_sp & 255u) == 0u) { if (xb_ld(&(bar)[XB_TMO])) break; if (_sp > XB_SPIN_CAP) { atomicAdd(&(bar)[XB_TMO], 1u); break; } } } } while (0)
; DEV void xcd_barrier(XcdBarrier& b) {
;   asm volatile("s_waitcnt vmcnt(0)" ::: "memory");
;   __syncthreads();
;   if (threadIdx.x == 0) {
;     unsigned* bar = b.bar;
;     __builtin_amdgcn_s_waitcnt(0);
;     const unsigned old = xb_add(&bar[XB_XSUB(b.x)], 1u);
;     const unsigned gen = b.round;
;     if (old + 1u == (gen + 1u) * b.nloc) {
;       __builtin_amdgcn_fence(__ATOMIC_RELEASE, "agent");
;       asm volatile("s_waitcnt vmcnt(0)" ::: "memory");
;       const unsigned og = xb_add(&bar[XB_TOP], 1u);
;       const unsigned tg = b.round;
;       if (og + 1u == (tg + 1u) * b.nx) xb_add(&bar[XB_TOPGEN], 1u);
;       else XB_SPIN(xb_ld(&bar[XB_TOPGEN]) == tg, bar);
;       __builtin_amdgcn_fence(__ATOMIC_ACQUIRE, "agent");
;       xb_add(&bar[XB_XGEN(b.x)], 1u);
;     } else {
;       XB_SPIN(xb_ld(&bar[XB_XGEN(b.x)]) == gen, bar);
;       __builtin_amdgcn_fence(__ATOMIC_ACQUIRE, "agent");
;     }
.LBB0_90:
	s_waitcnt vmcnt(0)
	s_waitcnt lgkmcnt(0)
	s_barrier
	s_mov_b64 s[0:1], exec
	v_readlane_b32 s2, v254, 12
	v_readlane_b32 s3, v254, 13
	s_and_b64 s[2:3], s[0:1], s[2:3]
	s_mov_b64 exec, s[2:3]
	s_cbranch_execz .LBB0_120
	v_readlane_b32 s2, v254, 32
	v_readlane_b32 s3, v254, 33
	s_waitcnt vmcnt(0) expcnt(0) lgkmcnt(0)
	s_add_i32 s21, s20, 1
	v_mov_b64_e32 v[0:1], s[2:3]
	flat_atomic_add v0, v[0:1], v174 sc0
	v_readlane_b32 s2, v255, 32
	s_mul_i32 s2, s21, s2
	s_waitcnt vmcnt(0) lgkmcnt(0)
	v_add_u32_e32 v0, 1, v0
	v_cmp_ne_u32_e32 vcc, s2, v0
	s_and_saveexec_b64 s[2:3], vcc
	s_xor_b64 s[2:3], exec, s[2:3]
	s_cbranch_execz .LBB0_104
	v_readlane_b32 s4, v254, 40
	v_readlane_b32 s5, v254, 41
	s_nop 1
	v_mov_b64_e32 v[0:1], s[4:5]
	flat_load_dword v0, v[0:1] sc1
	s_waitcnt vmcnt(0) lgkmcnt(0)
	v_cmp_eq_u32_e32 vcc, s20, v0
	s_and_saveexec_b64 s[4:5], vcc
	s_cbranch_execz .LBB0_103
	s_mov_b32 s22, 1
	s_mov_b64 s[6:7], 0
	s_branch .LBB0_95

; DEV unsigned xb_ld(unsigned* p) { return __hip_atomic_load(p, __ATOMIC_RELAXED, __HIP_MEMORY_SCOPE_AGENT); }
; #define XB_SPIN(cond, bar) do { unsigned _sp = 0; while (cond) { __builtin_amdgcn_s_sleep(1); \
;     if ((++_sp & 255u) == 0u) { if (xb_ld(&(bar)[XB_TMO])) break; if (_sp > XB_SPIN_CAP) { atomicAdd(&(bar)[XB_TMO], 1u); break; } } } } while (0)
; DEV void xcd_barrier(XcdBarrier& b) {
;     ...
;       XB_SPIN(xb_ld(&bar[XB_XGEN(b.x)]) == gen, bar);
;       __builtin_amdgcn_fence(__ATOMIC_ACQUIRE, "agent");
.LBB0_99:
	s_andn2_b64 s[10:11], s[10:11], exec
	s_and_b64 s[16:17], s[16:17], exec
	s_or_b64 s[10:11], s[10:11], s[16:17]
	s_and_saveexec_b64 s[16:17], s[14:15]
	s_cbranch_execz .LBB0_94
	v_readlane_b32 s12, v254, 40
	v_readlane_b32 s13, v254, 41
	s_add_i32 s22, s22, 1
	s_or_b64 s[10:11], s[10:11], exec
	v_mov_b64_e32 v[0:1], s[12:13]
	flat_load_dword v0, v[0:1] sc1
	s_waitcnt vmcnt(0) lgkmcnt(0)
	v_cmp_ne_u32_e32 vcc, s20, v0
	s_orn2_b64 s[12:13], vcc, exec
	s_branch .LBB0_94

; DEV unsigned xb_ld(unsigned* p) { return __hip_atomic_load(p, __ATOMIC_RELAXED, __HIP_MEMORY_SCOPE_AGENT); }
; DEV unsigned xb_add(unsigned* p, unsigned v) { return __hip_atomic_fetch_add(p, v, __ATOMIC_RELAXED, __HIP_MEMORY_SCOPE_AGENT); }
; #define XB_SPIN(cond, bar) do { unsigned _sp = 0; while (cond) { __builtin_amdgcn_s_sleep(1); \
;     if ((++_sp & 255u) == 0u) { if (xb_ld(&(bar)[XB_TMO])) break; if (_sp > XB_SPIN_CAP) { atomicAdd(&(bar)[XB_TMO], 1u); break; } } } } while (0)
; DEV void xcd_barrier(XcdBarrier& b) {
;   asm volatile("s_waitcnt vmcnt(0)" ::: "memory");
;   __syncthreads();
;   if (threadIdx.x == 0) {
;     unsigned* bar = b.bar;
;     __builtin_amdgcn_s_waitcnt(0);
;     const unsigned old = xb_add(&bar[XB_XSUB(b.x)], 1u);
;     const unsigned gen = b.round;
;     if (old + 1u == (gen + 1u) * b.nloc) {
;       __builtin_amdgcn_fence(__ATOMIC_RELEASE, "agent");
;       asm volatile("s_waitcnt vmcnt(0)" ::: "memory");
;       const unsigned og = xb_add(&bar[XB_TOP], 1u);
;       const unsigned tg = b.round;
;       if (og + 1u == (tg + 1u) * b.nx) xb_add(&bar[XB_TOPGEN], 1u);
;       else XB_SPIN(xb_ld(&bar[XB_TOPGEN]) == tg, bar);
;       __builtin_amdgcn_fence(__ATOMIC_ACQUIRE, "agent");
;       xb_add(&bar[XB_XGEN(b.x)], 1u);
;     } else {
;       XB_SPIN(xb_ld(&bar[XB_XGEN(b.x)]) == gen, bar);
;       __builtin_amdgcn_fence(__ATOMIC_ACQUIRE, "agent");
;     }
.LBB0_337:
	s_waitcnt vmcnt(0)
	s_waitcnt lgkmcnt(0)
	s_barrier
	s_mov_b64 s[0:1], exec
	v_readlane_b32 s2, v254, 12
	v_readlane_b32 s3, v254, 13
	s_and_b64 s[2:3], s[0:1], s[2:3]
	s_mov_b64 exec, s[2:3]
	s_cbranch_execz .LBB0_367
	v_readlane_b32 s2, v254, 32
	v_readlane_b32 s3, v254, 33
	s_waitcnt vmcnt(0) expcnt(0) lgkmcnt(0)
	s_nop 0
	v_mov_b64_e32 v[0:1], s[2:3]
	flat_atomic_add v0, v[0:1], v174 sc0
	v_readlane_b32 s2, v255, 51
	s_add_i32 s8, s2, 1
	v_readlane_b32 s2, v255, 32
	s_mul_i32 s2, s8, s2
	s_waitcnt vmcnt(0) lgkmcnt(0)
	v_add_u32_e32 v0, 1, v0
	v_cmp_ne_u32_e32 vcc, s2, v0
	s_and_saveexec_b64 s[2:3], vcc
	s_xor_b64 s[2:3], exec, s[2:3]
	s_cbranch_execz .LBB0_351
	v_readlane_b32 s6, v254, 40
	v_readlane_b32 s7, v254, 41
	s_nop 1
	v_mov_b64_e32 v[0:1], s[6:7]
	flat_load_dword v0, v[0:1] sc1
	v_readlane_b32 s6, v255, 51
	s_waitcnt vmcnt(0) lgkmcnt(0)
	s_nop 0
	v_cmp_eq_u32_e32 vcc, s6, v0
	s_and_saveexec_b64 s[6:7], vcc
	s_cbranch_execz .LBB0_350
	s_mov_b32 s9, 1
	s_mov_b64 s[10:11], 0
	s_branch .LBB0_342

; DEV unsigned xb_ld(unsigned* p) { return __hip_atomic_load(p, __ATOMIC_RELAXED, __HIP_MEMORY_SCOPE_AGENT); }
; #define XB_SPIN(cond, bar) do { unsigned _sp = 0; while (cond) { __builtin_amdgcn_s_sleep(1); \
;     if ((++_sp & 255u) == 0u) { if (xb_ld(&(bar)[XB_TMO])) break; if (_sp > XB_SPIN_CAP) { atomicAdd(&(bar)[XB_TMO], 1u); break; } } } } while (0)
; DEV void xcd_barrier(XcdBarrier& b) {
;     ...
;       XB_SPIN(xb_ld(&bar[XB_XGEN(b.x)]) == gen, bar);
;       __builtin_amdgcn_fence(__ATOMIC_ACQUIRE, "agent");
.LBB0_346:
	s_andn2_b64 s[14:15], s[14:15], exec
	s_and_b64 s[20:21], s[20:21], exec
	s_or_b64 s[14:15], s[14:15], s[20:21]
	s_and_saveexec_b64 s[20:21], s[18:19]
	s_cbranch_execz .LBB0_341
	v_readlane_b32 s16, v254, 40
	v_readlane_b32 s17, v254, 41
	s_add_i32 s9, s9, 1
	s_or_b64 s[14:15], s[14:15], exec
	v_mov_b64_e32 v[0:1], s[16:17]
	flat_load_dword v0, v[0:1] sc1
	v_readlane_b32 s16, v255, 51
	s_waitcnt vmcnt(0) lgkmcnt(0)
	s_nop 0
	v_cmp_ne_u32_e32 vcc, s16, v0
	s_orn2_b64 s[16:17], vcc, exec
	s_branch .LBB0_341

; DEV unsigned xb_ld(unsigned* p) { return __hip_atomic_load(p, __ATOMIC_RELAXED, __HIP_MEMORY_SCOPE_AGENT); }
; DEV unsigned xb_add(unsigned* p, unsigned v) { return __hip_atomic_fetch_add(p, v, __ATOMIC_RELAXED, __HIP_MEMORY_SCOPE_AGENT); }
; #define XB_SPIN(cond, bar) do { unsigned _sp = 0; while (cond) { __builtin_amdgcn_s_sleep(1); \
;     if ((++_sp & 255u) == 0u) { if (xb_ld(&(bar)[XB_TMO])) break; if (_sp > XB_SPIN_CAP) { atomicAdd(&(bar)[XB_TMO], 1u); break; } } } } while (0)
; DEV void xcd_barrier(XcdBarrier& b) {
;   asm volatile("s_waitcnt vmcnt(0)" ::: "memory");
;   __syncthreads();
;   if (threadIdx.x == 0) {
;     unsigned* bar = b.bar;
;     __builtin_amdgcn_s_waitcnt(0);
;     const unsigned old = xb_add(&bar[XB_XSUB(b.x)], 1u);
;     const unsigned gen = b.round;
;     if (old + 1u == (gen + 1u) * b.nloc) {
;       __builtin_amdgcn_fence(__ATOMIC_RELEASE, "agent");
;       asm volatile("s_waitcnt vmcnt(0)" ::: "memory");
;       const unsigned og = xb_add(&bar[XB_TOP], 1u);
;       const unsigned tg = b.round;
;       if (og + 1u == (tg + 1u) * b.nx) xb_add(&bar[XB_TOPGEN], 1u);
;       else XB_SPIN(xb_ld(&bar[XB_TOPGEN]) == tg, bar);
;       __builtin_amdgcn_fence(__ATOMIC_ACQUIRE, "agent");
;       xb_add(&bar[XB_XGEN(b.x)], 1u);
;     } else {
;       XB_SPIN(xb_ld(&bar[XB_XGEN(b.x)]) == gen, bar);
;       __builtin_amdgcn_fence(__ATOMIC_ACQUIRE, "agent");
;     }
.LBB0_404:
	s_waitcnt vmcnt(0)
	s_waitcnt lgkmcnt(0)
	s_barrier
	s_mov_b64 s[0:1], exec
	v_readlane_b32 s2, v254, 12
	v_readlane_b32 s3, v254, 13
	s_and_b64 s[2:3], s[0:1], s[2:3]
	s_mov_b64 exec, s[2:3]
	s_cbranch_execz .LBB0_435
	v_readlane_b32 s2, v254, 32
	v_readlane_b32 s3, v254, 33
	s_waitcnt vmcnt(0) expcnt(0) lgkmcnt(0)
	s_nop 0
	v_mov_b64_e32 v[0:1], s[2:3]
	flat_atomic_add v0, v[0:1], v174 sc0
	v_readlane_b32 s2, v255, 51
	s_add_i32 s23, s2, 2
	v_readlane_b32 s2, v255, 32
	s_mul_i32 s2, s23, s2
	s_waitcnt vmcnt(0) lgkmcnt(0)
	v_add_u32_e32 v0, 1, v0
	v_cmp_ne_u32_e32 vcc, s2, v0
	s_and_saveexec_b64 s[2:3], vcc
	s_xor_b64 s[2:3], exec, s[2:3]
	s_cbranch_execz .LBB0_419
	v_readlane_b32 s6, v254, 40
	v_readlane_b32 s7, v254, 41
	s_nop 1
	v_mov_b64_e32 v[0:1], s[6:7]
	flat_load_dword v0, v[0:1] sc1
	s_waitcnt vmcnt(0) lgkmcnt(0)
	v_cmp_eq_u32_e32 vcc, s22, v0
	s_and_saveexec_b64 s[6:7], vcc
	s_cbranch_execz .LBB0_418
	s_mov_b32 s44, 1
	s_mov_b64 s[8:9], 0
	s_branch .LBB0_409

; DEV unsigned xb_ld(unsigned* p) { return __hip_atomic_load(p, __ATOMIC_RELAXED, __HIP_MEMORY_SCOPE_AGENT); }
; #define XB_SPIN(cond, bar) do { unsigned _sp = 0; while (cond) { __builtin_amdgcn_s_sleep(1); \
;     if ((++_sp & 255u) == 0u) { if (xb_ld(&(bar)[XB_TMO])) break; if (_sp > XB_SPIN_CAP) { atomicAdd(&(bar)[XB_TMO], 1u); break; } } } } while (0)
; DEV void xcd_barrier(XcdBarrier& b) {
;     ...
;       XB_SPIN(xb_ld(&bar[XB_XGEN(b.x)]) == gen, bar);
;       __builtin_amdgcn_fence(__ATOMIC_ACQUIRE, "agent");
.LBB0_413:
	s_andn2_b64 s[12:13], s[12:13], exec
	s_and_b64 s[18:19], s[18:19], exec
	s_or_b64 s[12:13], s[12:13], s[18:19]
	s_and_saveexec_b64 s[18:19], s[16:17]
	s_cbranch_execz .LBB0_408
	v_readlane_b32 s14, v254, 40
	v_readlane_b32 s15, v254, 41
	s_add_i32 s44, s44, 1
	s_or_b64 s[12:13], s[12:13], exec
	v_mov_b64_e32 v[0:1], s[14:15]
	flat_load_dword v0, v[0:1] sc1
	s_waitcnt vmcnt(0) lgkmcnt(0)
	v_cmp_ne_u32_e32 vcc, s22, v0
	s_orn2_b64 s[14:15], vcc, exec
	s_branch .LBB0_408

; DEV unsigned xb_ld(unsigned* p) { return __hip_atomic_load(p, __ATOMIC_RELAXED, __HIP_MEMORY_SCOPE_AGENT); }
; DEV unsigned xb_add(unsigned* p, unsigned v) { return __hip_atomic_fetch_add(p, v, __ATOMIC_RELAXED, __HIP_MEMORY_SCOPE_AGENT); }
; #define XB_SPIN(cond, bar) do { unsigned _sp = 0; while (cond) { __builtin_amdgcn_s_sleep(1); \
;     if ((++_sp & 255u) == 0u) { if (xb_ld(&(bar)[XB_TMO])) break; if (_sp > XB_SPIN_CAP) { atomicAdd(&(bar)[XB_TMO], 1u); break; } } } } while (0)
; DEV void xcd_barrier(XcdBarrier& b) {
;   asm volatile("s_waitcnt vmcnt(0)" ::: "memory");
;   __syncthreads();
;   if (threadIdx.x == 0) {
;     unsigned* bar = b.bar;
;     __builtin_amdgcn_s_waitcnt(0);
;     const unsigned old = xb_add(&bar[XB_XSUB(b.x)], 1u);
;     const unsigned gen = b.round;
;     if (old + 1u == (gen + 1u) * b.nloc) {
;       __builtin_amdgcn_fence(__ATOMIC_RELEASE, "agent");
;       asm volatile("s_waitcnt vmcnt(0)" ::: "memory");
;       const unsigned og = xb_add(&bar[XB_TOP], 1u);
;       const unsigned tg = b.round;
;       if (og + 1u == (tg + 1u) * b.nx) xb_add(&bar[XB_TOPGEN], 1u);
;       else XB_SPIN(xb_ld(&bar[XB_TOPGEN]) == tg, bar);
;       __builtin_amdgcn_fence(__ATOMIC_ACQUIRE, "agent");
;       xb_add(&bar[XB_XGEN(b.x)], 1u);
;     } else {
;       XB_SPIN(xb_ld(&bar[XB_XGEN(b.x)]) == gen, bar);
;       __builtin_amdgcn_fence(__ATOMIC_ACQUIRE, "agent");
;     }
.LBB0_443:
	s_waitcnt vmcnt(0)
	s_add_i32 s0, s22, 1
	v_writelane_b32 v255, s0, 55
	s_waitcnt lgkmcnt(0)
	s_barrier
	s_mov_b64 s[0:1], exec
	v_readlane_b32 s2, v254, 12
	v_readlane_b32 s3, v254, 13
	s_and_b64 s[2:3], s[0:1], s[2:3]
	s_mov_b64 exec, s[2:3]
	s_cbranch_execz .LBB0_473
	v_readlane_b32 s2, v254, 32
	v_readlane_b32 s3, v254, 33
	s_waitcnt vmcnt(0) expcnt(0) lgkmcnt(0)
	s_add_i32 s22, s22, 2
	v_mov_b64_e32 v[0:1], s[2:3]
	flat_atomic_add v0, v[0:1], v174 sc0
	v_readlane_b32 s2, v255, 32
	s_mul_i32 s2, s22, s2
	s_waitcnt vmcnt(0) lgkmcnt(0)
	v_add_u32_e32 v0, 1, v0
	v_cmp_ne_u32_e32 vcc, s2, v0
	s_and_saveexec_b64 s[2:3], vcc
	s_xor_b64 s[2:3], exec, s[2:3]
	s_cbranch_execz .LBB0_457
	v_readlane_b32 s6, v254, 40
	v_readlane_b32 s7, v254, 41
	s_nop 1
	v_mov_b64_e32 v[0:1], s[6:7]
	flat_load_dword v0, v[0:1] sc1
	v_readlane_b32 s6, v255, 55
	s_waitcnt vmcnt(0) lgkmcnt(0)
	s_nop 0
	v_cmp_eq_u32_e32 vcc, s6, v0
	s_and_saveexec_b64 s[6:7], vcc
	s_cbranch_execz .LBB0_456
	s_mov_b32 s44, 1
	s_mov_b64 s[8:9], 0
	s_branch .LBB0_448

; DEV unsigned xb_ld(unsigned* p) { return __hip_atomic_load(p, __ATOMIC_RELAXED, __HIP_MEMORY_SCOPE_AGENT); }
; #define XB_SPIN(cond, bar) do { unsigned _sp = 0; while (cond) { __builtin_amdgcn_s_sleep(1); \
;     if ((++_sp & 255u) == 0u) { if (xb_ld(&(bar)[XB_TMO])) break; if (_sp > XB_SPIN_CAP) { atomicAdd(&(bar)[XB_TMO], 1u); break; } } } } while (0)
; DEV void xcd_barrier(XcdBarrier& b) {
;     ...
;       XB_SPIN(xb_ld(&bar[XB_XGEN(b.x)]) == gen, bar);
;       __builtin_amdgcn_fence(__ATOMIC_ACQUIRE, "agent");
.LBB0_452:
	s_andn2_b64 s[12:13], s[12:13], exec
	s_and_b64 s[18:19], s[18:19], exec
	s_or_b64 s[12:13], s[12:13], s[18:19]
	s_and_saveexec_b64 s[18:19], s[16:17]
	s_cbranch_execz .LBB0_447
	v_readlane_b32 s14, v254, 40
	v_readlane_b32 s15, v254, 41
	s_add_i32 s44, s44, 1
	s_or_b64 s[12:13], s[12:13], exec
	v_mov_b64_e32 v[0:1], s[14:15]
	flat_load_dword v0, v[0:1] sc1
	v_readlane_b32 s14, v255, 55
	s_waitcnt vmcnt(0) lgkmcnt(0)
	s_nop 0
	v_cmp_ne_u32_e32 vcc, s14, v0
	s_orn2_b64 s[14:15], vcc, exec
	s_branch .LBB0_447

; DEV unsigned xb_ld(unsigned* p) { return __hip_atomic_load(p, __ATOMIC_RELAXED, __HIP_MEMORY_SCOPE_AGENT); }
; DEV unsigned xb_add(unsigned* p, unsigned v) { return __hip_atomic_fetch_add(p, v, __ATOMIC_RELAXED, __HIP_MEMORY_SCOPE_AGENT); }
; #define XB_SPIN(cond, bar) do { unsigned _sp = 0; while (cond) { __builtin_amdgcn_s_sleep(1); \
;     if ((++_sp & 255u) == 0u) { if (xb_ld(&(bar)[XB_TMO])) break; if (_sp > XB_SPIN_CAP) { atomicAdd(&(bar)[XB_TMO], 1u); break; } } } } while (0)
; DEV void xcd_barrier(XcdBarrier& b) {
;   asm volatile("s_waitcnt vmcnt(0)" ::: "memory");
;   __syncthreads();
;   if (threadIdx.x == 0) {
;     unsigned* bar = b.bar;
;     __builtin_amdgcn_s_waitcnt(0);
;     const unsigned old = xb_add(&bar[XB_XSUB(b.x)], 1u);
;     const unsigned gen = b.round;
;     if (old + 1u == (gen + 1u) * b.nloc) {
;       __builtin_amdgcn_fence(__ATOMIC_RELEASE, "agent");
;       asm volatile("s_waitcnt vmcnt(0)" ::: "memory");
;       const unsigned og = xb_add(&bar[XB_TOP], 1u);
;       const unsigned tg = b.round;
;       if (og + 1u == (tg + 1u) * b.nx) xb_add(&bar[XB_TOPGEN], 1u);
;       else XB_SPIN(xb_ld(&bar[XB_TOPGEN]) == tg, bar);
;       __builtin_amdgcn_fence(__ATOMIC_ACQUIRE, "agent");
;       xb_add(&bar[XB_XGEN(b.x)], 1u);
;     } else {
;       XB_SPIN(xb_ld(&bar[XB_XGEN(b.x)]) == gen, bar);
;       __builtin_amdgcn_fence(__ATOMIC_ACQUIRE, "agent");
;     }
.LBB0_507:
	s_waitcnt vmcnt(0)
	v_readlane_b32 s4, v255, 55
	s_add_i32 s20, s4, 1
	s_waitcnt lgkmcnt(0)
	s_barrier
	s_mov_b64 s[0:1], exec
	v_readlane_b32 s2, v254, 12
	v_readlane_b32 s3, v254, 13
	s_and_b64 s[2:3], s[0:1], s[2:3]
	s_mov_b64 exec, s[2:3]
	s_cbranch_execz .LBB0_537
	v_readlane_b32 s2, v254, 32
	v_readlane_b32 s3, v254, 33
	s_waitcnt vmcnt(0) expcnt(0) lgkmcnt(0)
	s_add_i32 s21, s4, 2
	v_mov_b64_e32 v[0:1], s[2:3]
	flat_atomic_add v0, v[0:1], v174 sc0
	v_readlane_b32 s2, v255, 32
	s_mul_i32 s2, s21, s2
	s_waitcnt vmcnt(0) lgkmcnt(0)
	v_add_u32_e32 v0, 1, v0
	v_cmp_ne_u32_e32 vcc, s2, v0
	s_and_saveexec_b64 s[2:3], vcc
	s_xor_b64 s[2:3], exec, s[2:3]
	s_cbranch_execz .LBB0_521
	v_readlane_b32 s4, v254, 40
	v_readlane_b32 s5, v254, 41
	s_nop 1
	v_mov_b64_e32 v[0:1], s[4:5]
	flat_load_dword v0, v[0:1] sc1
	s_waitcnt vmcnt(0) lgkmcnt(0)
	v_cmp_eq_u32_e32 vcc, s20, v0
	s_and_saveexec_b64 s[4:5], vcc
	s_cbranch_execz .LBB0_520
	s_mov_b32 s22, 1
	s_mov_b64 s[6:7], 0
	s_branch .LBB0_512

; DEV unsigned xb_ld(unsigned* p) { return __hip_atomic_load(p, __ATOMIC_RELAXED, __HIP_MEMORY_SCOPE_AGENT); }
; DEV unsigned xb_add(unsigned* p, unsigned v) { return __hip_atomic_fetch_add(p, v, __ATOMIC_RELAXED, __HIP_MEMORY_SCOPE_AGENT); }
; #define XB_SPIN(cond, bar) do { unsigned _sp = 0; while (cond) { __builtin_amdgcn_s_sleep(1); \
;     if ((++_sp & 255u) == 0u) { if (xb_ld(&(bar)[XB_TMO])) break; if (_sp > XB_SPIN_CAP) { atomicAdd(&(bar)[XB_TMO], 1u); break; } } } } while (0)
; DEV void xcd_barrier(XcdBarrier& b) {
;   asm volatile("s_waitcnt vmcnt(0)" ::: "memory");
;   __syncthreads();
;   if (threadIdx.x == 0) {
;     unsigned* bar = b.bar;
;     __builtin_amdgcn_s_waitcnt(0);
;     const unsigned old = xb_add(&bar[XB_XSUB(b.x)], 1u);
;     const unsigned gen = b.round;
;     if (old + 1u == (gen + 1u) * b.nloc) {
;       __builtin_amdgcn_fence(__ATOMIC_RELEASE, "agent");
;       asm volatile("s_waitcnt vmcnt(0)" ::: "memory");
;       const unsigned og = xb_add(&bar[XB_TOP], 1u);
;       const unsigned tg = b.round;
;       if (og + 1u == (tg + 1u) * b.nx) xb_add(&bar[XB_TOPGEN], 1u);
;       else XB_SPIN(xb_ld(&bar[XB_TOPGEN]) == tg, bar);
;       __builtin_amdgcn_fence(__ATOMIC_ACQUIRE, "agent");
;       xb_add(&bar[XB_XGEN(b.x)], 1u);
;     } else {
;       XB_SPIN(xb_ld(&bar[XB_XGEN(b.x)]) == gen, bar);
;       __builtin_amdgcn_fence(__ATOMIC_ACQUIRE, "agent");
;     }
.LBB0_539:
	s_waitcnt vmcnt(0)
	s_add_i32 s21, s20, 1
	s_waitcnt lgkmcnt(0)
	s_barrier
	s_mov_b64 s[0:1], exec
	v_readlane_b32 s2, v254, 12
	v_readlane_b32 s3, v254, 13
	s_and_b64 s[2:3], s[0:1], s[2:3]
	s_mov_b64 exec, s[2:3]
	s_cbranch_execz .LBB0_569
	v_readlane_b32 s2, v254, 32
	v_readlane_b32 s3, v254, 33
	s_waitcnt vmcnt(0) expcnt(0) lgkmcnt(0)
	s_add_i32 s20, s20, 2
	v_mov_b64_e32 v[0:1], s[2:3]
	flat_atomic_add v0, v[0:1], v174 sc0
	v_readlane_b32 s2, v255, 32
	s_mul_i32 s2, s20, s2
	s_waitcnt vmcnt(0) lgkmcnt(0)
	v_add_u32_e32 v0, 1, v0
	v_cmp_ne_u32_e32 vcc, s2, v0
	s_and_saveexec_b64 s[2:3], vcc
	s_xor_b64 s[2:3], exec, s[2:3]
	s_cbranch_execz .LBB0_553
	v_readlane_b32 s4, v254, 40
	v_readlane_b32 s5, v254, 41
	s_nop 1
	v_mov_b64_e32 v[0:1], s[4:5]
	flat_load_dword v0, v[0:1] sc1
	s_waitcnt vmcnt(0) lgkmcnt(0)
	v_cmp_eq_u32_e32 vcc, s21, v0
	s_and_saveexec_b64 s[4:5], vcc
	s_cbranch_execz .LBB0_552
	s_mov_b32 s22, 1
	s_mov_b64 s[6:7], 0
	s_branch .LBB0_544

; DEV unsigned xb_ld(unsigned* p) { return __hip_atomic_load(p, __ATOMIC_RELAXED, __HIP_MEMORY_SCOPE_AGENT); }
; #define XB_SPIN(cond, bar) do { unsigned _sp = 0; while (cond) { __builtin_amdgcn_s_sleep(1); \
;     if ((++_sp & 255u) == 0u) { if (xb_ld(&(bar)[XB_TMO])) break; if (_sp > XB_SPIN_CAP) { atomicAdd(&(bar)[XB_TMO], 1u); break; } } } } while (0)
; DEV void xcd_barrier(XcdBarrier& b) {
;     ...
;       XB_SPIN(xb_ld(&bar[XB_XGEN(b.x)]) == gen, bar);
;       __builtin_amdgcn_fence(__ATOMIC_ACQUIRE, "agent");
.LBB0_548:
	s_andn2_b64 s[10:11], s[10:11], exec
	s_and_b64 s[16:17], s[16:17], exec
	s_or_b64 s[10:11], s[10:11], s[16:17]
	s_and_saveexec_b64 s[16:17], s[14:15]
	s_cbranch_execz .LBB0_543
	v_readlane_b32 s12, v254, 40
	v_readlane_b32 s13, v254, 41
	s_add_i32 s22, s22, 1
	s_or_b64 s[10:11], s[10:11], exec
	v_mov_b64_e32 v[0:1], s[12:13]
	flat_load_dword v0, v[0:1] sc1
	s_waitcnt vmcnt(0) lgkmcnt(0)
	v_cmp_ne_u32_e32 vcc, s21, v0
	s_orn2_b64 s[12:13], vcc, exec
	s_branch .LBB0_543

; DEV unsigned xb_ld(unsigned* p) { return __hip_atomic_load(p, __ATOMIC_RELAXED, __HIP_MEMORY_SCOPE_AGENT); }
; DEV unsigned xb_add(unsigned* p, unsigned v) { return __hip_atomic_fetch_add(p, v, __ATOMIC_RELAXED, __HIP_MEMORY_SCOPE_AGENT); }
; #define XB_SPIN(cond, bar) do { unsigned _sp = 0; while (cond) { __builtin_amdgcn_s_sleep(1); \
;     if ((++_sp & 255u) == 0u) { if (xb_ld(&(bar)[XB_TMO])) break; if (_sp > XB_SPIN_CAP) { atomicAdd(&(bar)[XB_TMO], 1u); break; } } } } while (0)
; DEV void xcd_barrier(XcdBarrier& b) {
;   asm volatile("s_waitcnt vmcnt(0)" ::: "memory");
;   __syncthreads();
;   if (threadIdx.x == 0) {
;     unsigned* bar = b.bar;
;     __builtin_amdgcn_s_waitcnt(0);
;     const unsigned old = xb_add(&bar[XB_XSUB(b.x)], 1u);
;     const unsigned gen = b.round;
;     if (old + 1u == (gen + 1u) * b.nloc) {
;       __builtin_amdgcn_fence(__ATOMIC_RELEASE, "agent");
;       asm volatile("s_waitcnt vmcnt(0)" ::: "memory");
;       const unsigned og = xb_add(&bar[XB_TOP], 1u);
;       const unsigned tg = b.round;
;       if (og + 1u == (tg + 1u) * b.nx) xb_add(&bar[XB_TOPGEN], 1u);
;       else XB_SPIN(xb_ld(&bar[XB_TOPGEN]) == tg, bar);
;       __builtin_amdgcn_fence(__ATOMIC_ACQUIRE, "agent");
;       xb_add(&bar[XB_XGEN(b.x)], 1u);
;     } else {
;       XB_SPIN(xb_ld(&bar[XB_XGEN(b.x)]) == gen, bar);
;       __builtin_amdgcn_fence(__ATOMIC_ACQUIRE, "agent");
;     }
.LBB0_575:
	s_waitcnt vmcnt(0)
	s_mov_b64 s[80:81], 0x32eb0000
	s_mov_b32 s79, 0x32eb3000
	s_mov_b32 s78, 0x32eb2000
	s_mov_b32 s77, 0x32eb1000
	s_mov_b32 s76, 0x800000
	s_waitcnt lgkmcnt(0)
	s_barrier
	s_mov_b64 s[0:1], exec
	v_readlane_b32 s2, v254, 12
	v_readlane_b32 s3, v254, 13
	s_and_b64 s[2:3], s[0:1], s[2:3]
	s_mov_b64 exec, s[2:3]
	s_cbranch_execz .LBB0_605
	v_readlane_b32 s2, v254, 32
	v_readlane_b32 s3, v254, 33
	s_waitcnt vmcnt(0) expcnt(0) lgkmcnt(0)
	s_nop 0
	v_mov_b64_e32 v[0:1], s[2:3]
	flat_atomic_add v0, v[0:1], v174 sc0
	v_readlane_b32 s2, v255, 51
	s_add_i32 s22, s2, 1
	v_readlane_b32 s2, v255, 32
	s_mul_i32 s2, s22, s2
	s_waitcnt vmcnt(0) lgkmcnt(0)
	v_add_u32_e32 v0, 1, v0
	v_cmp_ne_u32_e32 vcc, s2, v0
	s_and_saveexec_b64 s[2:3], vcc
	s_xor_b64 s[2:3], exec, s[2:3]
	s_cbranch_execz .LBB0_589
	v_readlane_b32 s6, v254, 40
	v_readlane_b32 s7, v254, 41
	s_nop 1
	v_mov_b64_e32 v[0:1], s[6:7]
	flat_load_dword v0, v[0:1] sc1
	v_readlane_b32 s6, v255, 51
	s_waitcnt vmcnt(0) lgkmcnt(0)
	s_nop 0
	v_cmp_eq_u32_e32 vcc, s6, v0
	s_and_saveexec_b64 s[6:7], vcc
	s_cbranch_execz .LBB0_588
	s_mov_b32 s23, 1
	s_mov_b64 s[8:9], 0
	s_branch .LBB0_580

; DEV unsigned xb_ld(unsigned* p) { return __hip_atomic_load(p, __ATOMIC_RELAXED, __HIP_MEMORY_SCOPE_AGENT); }
; #define XB_SPIN(cond, bar) do { unsigned _sp = 0; while (cond) { __builtin_amdgcn_s_sleep(1); \
;     if ((++_sp & 255u) == 0u) { if (xb_ld(&(bar)[XB_TMO])) break; if (_sp > XB_SPIN_CAP) { atomicAdd(&(bar)[XB_TMO], 1u); break; } } } } while (0)
; DEV void xcd_barrier(XcdBarrier& b) {
;     ...
;       XB_SPIN(xb_ld(&bar[XB_XGEN(b.x)]) == gen, bar);
;       __builtin_amdgcn_fence(__ATOMIC_ACQUIRE, "agent");
.LBB0_584:
	s_andn2_b64 s[12:13], s[12:13], exec
	s_and_b64 s[18:19], s[18:19], exec
	s_or_b64 s[12:13], s[12:13], s[18:19]
	s_and_saveexec_b64 s[18:19], s[16:17]
	s_cbranch_execz .LBB0_579
	v_readlane_b32 s14, v254, 40
	v_readlane_b32 s15, v254, 41
	s_add_i32 s23, s23, 1
	s_or_b64 s[12:13], s[12:13], exec
	v_mov_b64_e32 v[0:1], s[14:15]
	flat_load_dword v0, v[0:1] sc1
	v_readlane_b32 s14, v255, 51
	s_waitcnt vmcnt(0) lgkmcnt(0)
	s_nop 0
	v_cmp_ne_u32_e32 vcc, s14, v0
	s_orn2_b64 s[14:15], vcc, exec
	s_branch .LBB0_579

; DEV unsigned xb_ld(unsigned* p) { return __hip_atomic_load(p, __ATOMIC_RELAXED, __HIP_MEMORY_SCOPE_AGENT); }
; DEV unsigned xb_add(unsigned* p, unsigned v) { return __hip_atomic_fetch_add(p, v, __ATOMIC_RELAXED, __HIP_MEMORY_SCOPE_AGENT); }
; #define XB_SPIN(cond, bar) do { unsigned _sp = 0; while (cond) { __builtin_amdgcn_s_sleep(1); \
;     if ((++_sp & 255u) == 0u) { if (xb_ld(&(bar)[XB_TMO])) break; if (_sp > XB_SPIN_CAP) { atomicAdd(&(bar)[XB_TMO], 1u); break; } } } } while (0)
; DEV void xcd_barrier(XcdBarrier& b) {
;   asm volatile("s_waitcnt vmcnt(0)" ::: "memory");
;   __syncthreads();
;   if (threadIdx.x == 0) {
;     unsigned* bar = b.bar;
;     __builtin_amdgcn_s_waitcnt(0);
;     const unsigned old = xb_add(&bar[XB_XSUB(b.x)], 1u);
;     const unsigned gen = b.round;
;     if (old + 1u == (gen + 1u) * b.nloc) {
;       __builtin_amdgcn_fence(__ATOMIC_RELEASE, "agent");
;       asm volatile("s_waitcnt vmcnt(0)" ::: "memory");
;       const unsigned og = xb_add(&bar[XB_TOP], 1u);
;       const unsigned tg = b.round;
;       if (og + 1u == (tg + 1u) * b.nx) xb_add(&bar[XB_TOPGEN], 1u);
;       else XB_SPIN(xb_ld(&bar[XB_TOPGEN]) == tg, bar);
;       __builtin_amdgcn_fence(__ATOMIC_ACQUIRE, "agent");
;       xb_add(&bar[XB_XGEN(b.x)], 1u);
;     } else {
;       XB_SPIN(xb_ld(&bar[XB_XGEN(b.x)]) == gen, bar);
;       __builtin_amdgcn_fence(__ATOMIC_ACQUIRE, "agent");
;     }
.LBB0_606:
	s_waitcnt vmcnt(0)
	v_readlane_b32 s6, v255, 51
	s_add_i32 s22, s6, 1
	s_waitcnt lgkmcnt(0)
	s_barrier
	s_mov_b64 s[0:1], exec
	v_readlane_b32 s2, v254, 12
	v_readlane_b32 s3, v254, 13
	s_and_b64 s[2:3], s[0:1], s[2:3]
	s_mov_b64 exec, s[2:3]
	s_cbranch_execz .LBB0_653
	v_readlane_b32 s2, v254, 32
	v_readlane_b32 s3, v254, 33
	s_waitcnt vmcnt(0) expcnt(0) lgkmcnt(0)
	s_add_i32 s23, s6, 2
	v_mov_b64_e32 v[0:1], s[2:3]
	flat_atomic_add v0, v[0:1], v174 sc0
	v_readlane_b32 s2, v255, 32
	s_mul_i32 s2, s23, s2
	s_waitcnt vmcnt(0) lgkmcnt(0)
	v_add_u32_e32 v0, 1, v0
	v_cmp_ne_u32_e32 vcc, s2, v0
	s_and_saveexec_b64 s[2:3], vcc
	s_xor_b64 s[2:3], exec, s[2:3]
	s_cbranch_execz .LBB0_637
	v_readlane_b32 s6, v254, 40
	v_readlane_b32 s7, v254, 41
	s_nop 1
	v_mov_b64_e32 v[0:1], s[6:7]
	flat_load_dword v0, v[0:1] sc1
	s_waitcnt vmcnt(0) lgkmcnt(0)
	v_cmp_eq_u32_e32 vcc, s22, v0
	s_and_saveexec_b64 s[6:7], vcc
	s_cbranch_execz .LBB0_636
	s_mov_b32 s44, 1
	s_mov_b64 s[8:9], 0
	s_branch .LBB0_628

; DEV unsigned xb_ld(unsigned* p) { return __hip_atomic_load(p, __ATOMIC_RELAXED, __HIP_MEMORY_SCOPE_AGENT); }
; DEV unsigned xb_add(unsigned* p, unsigned v) { return __hip_atomic_fetch_add(p, v, __ATOMIC_RELAXED, __HIP_MEMORY_SCOPE_AGENT); }
; #define XB_SPIN(cond, bar) do { unsigned _sp = 0; while (cond) { __builtin_amdgcn_s_sleep(1); \
;     if ((++_sp & 255u) == 0u) { if (xb_ld(&(bar)[XB_TMO])) break; if (_sp > XB_SPIN_CAP) { atomicAdd(&(bar)[XB_TMO], 1u); break; } } } } while (0)
; DEV void xcd_barrier(XcdBarrier& b) {
;   asm volatile("s_waitcnt vmcnt(0)" ::: "memory");
;   __syncthreads();
;   if (threadIdx.x == 0) {
;     unsigned* bar = b.bar;
;     __builtin_amdgcn_s_waitcnt(0);
;     const unsigned old = xb_add(&bar[XB_XSUB(b.x)], 1u);
;     const unsigned gen = b.round;
;     if (old + 1u == (gen + 1u) * b.nloc) {
;       __builtin_amdgcn_fence(__ATOMIC_RELEASE, "agent");
;       asm volatile("s_waitcnt vmcnt(0)" ::: "memory");
;       const unsigned og = xb_add(&bar[XB_TOP], 1u);
;       const unsigned tg = b.round;
;       if (og + 1u == (tg + 1u) * b.nx) xb_add(&bar[XB_TOPGEN], 1u);
;       else XB_SPIN(xb_ld(&bar[XB_TOPGEN]) == tg, bar);
;       __builtin_amdgcn_fence(__ATOMIC_ACQUIRE, "agent");
;       xb_add(&bar[XB_XGEN(b.x)], 1u);
;     } else {
;       XB_SPIN(xb_ld(&bar[XB_XGEN(b.x)]) == gen, bar);
;       __builtin_amdgcn_fence(__ATOMIC_ACQUIRE, "agent");
;     }
.LBB0_654:
	s_waitcnt vmcnt(0)
	s_add_i32 s23, s22, 1
	s_waitcnt lgkmcnt(0)
	s_barrier
	s_mov_b64 s[0:1], exec
	v_readlane_b32 s2, v254, 12
	v_readlane_b32 s3, v254, 13
	s_and_b64 s[2:3], s[0:1], s[2:3]
	s_mov_b64 exec, s[2:3]
	s_cbranch_execz .LBB0_706
	v_readlane_b32 s2, v254, 32
	v_readlane_b32 s3, v254, 33
	s_waitcnt vmcnt(0) expcnt(0) lgkmcnt(0)
	s_add_i32 s22, s22, 2
	v_mov_b64_e32 v[0:1], s[2:3]
	flat_atomic_add v0, v[0:1], v174 sc0
	v_readlane_b32 s2, v255, 32
	s_mul_i32 s2, s22, s2
	s_waitcnt vmcnt(0) lgkmcnt(0)
	v_add_u32_e32 v0, 1, v0
	v_cmp_ne_u32_e32 vcc, s2, v0
	s_and_saveexec_b64 s[2:3], vcc
	s_xor_b64 s[2:3], exec, s[2:3]
	s_cbranch_execz .LBB0_690
	v_readlane_b32 s6, v254, 40
	v_readlane_b32 s7, v254, 41
	s_nop 1
	v_mov_b64_e32 v[0:1], s[6:7]
	flat_load_dword v0, v[0:1] sc1
	s_waitcnt vmcnt(0) lgkmcnt(0)
	v_cmp_eq_u32_e32 vcc, s23, v0
	s_and_saveexec_b64 s[6:7], vcc
	s_cbranch_execz .LBB0_689
	s_mov_b32 s44, 1
	s_mov_b64 s[8:9], 0
	s_branch .LBB0_681

; DEV unsigned xb_ld(unsigned* p) { return __hip_atomic_load(p, __ATOMIC_RELAXED, __HIP_MEMORY_SCOPE_AGENT); }
; #define XB_SPIN(cond, bar) do { unsigned _sp = 0; while (cond) { __builtin_amdgcn_s_sleep(1); \
;     if ((++_sp & 255u) == 0u) { if (xb_ld(&(bar)[XB_TMO])) break; if (_sp > XB_SPIN_CAP) { atomicAdd(&(bar)[XB_TMO], 1u); break; } } } } while (0)
; DEV void xcd_barrier(XcdBarrier& b) {
;     ...
;       XB_SPIN(xb_ld(&bar[XB_XGEN(b.x)]) == gen, bar);
;       __builtin_amdgcn_fence(__ATOMIC_ACQUIRE, "agent");
.LBB0_685:
	s_andn2_b64 s[12:13], s[12:13], exec
	s_and_b64 s[18:19], s[18:19], exec
	s_or_b64 s[12:13], s[12:13], s[18:19]
	s_and_saveexec_b64 s[18:19], s[16:17]
	s_cbranch_execz .LBB0_680
	v_readlane_b32 s14, v254, 40
	v_readlane_b32 s15, v254, 41
	s_add_i32 s44, s44, 1
	s_or_b64 s[12:13], s[12:13], exec
	v_mov_b64_e32 v[0:1], s[14:15]
	flat_load_dword v0, v[0:1] sc1
	s_waitcnt vmcnt(0) lgkmcnt(0)
	v_cmp_ne_u32_e32 vcc, s23, v0
	s_orn2_b64 s[14:15], vcc, exec
	s_branch .LBB0_680

; DEV unsigned xb_ld(unsigned* p) { return __hip_atomic_load(p, __ATOMIC_RELAXED, __HIP_MEMORY_SCOPE_AGENT); }
; DEV unsigned xb_add(unsigned* p, unsigned v) { return __hip_atomic_fetch_add(p, v, __ATOMIC_RELAXED, __HIP_MEMORY_SCOPE_AGENT); }
; #define XB_SPIN(cond, bar) do { unsigned _sp = 0; while (cond) { __builtin_amdgcn_s_sleep(1); \
;     if ((++_sp & 255u) == 0u) { if (xb_ld(&(bar)[XB_TMO])) break; if (_sp > XB_SPIN_CAP) { atomicAdd(&(bar)[XB_TMO], 1u); break; } } } } while (0)
; DEV void xcd_barrier(XcdBarrier& b) {
;     ...
;     unsigned* bar = b.bar;
;     __builtin_amdgcn_s_waitcnt(0);
;     const unsigned old = xb_add(&bar[XB_XSUB(b.x)], 1u);
;     const unsigned gen = b.round;
;     if (old + 1u == (gen + 1u) * b.nloc) {
;       __builtin_amdgcn_fence(__ATOMIC_RELEASE, "agent");
;       asm volatile("s_waitcnt vmcnt(0)" ::: "memory");
;       const unsigned og = xb_add(&bar[XB_TOP], 1u);
;       const unsigned tg = b.round;
;       if (og + 1u == (tg + 1u) * b.nx) xb_add(&bar[XB_TOPGEN], 1u);
;       else XB_SPIN(xb_ld(&bar[XB_TOPGEN]) == tg, bar);
;       __builtin_amdgcn_fence(__ATOMIC_ACQUIRE, "agent");
;       xb_add(&bar[XB_XGEN(b.x)], 1u);
;     } else {
;       XB_SPIN(xb_ld(&bar[XB_XGEN(b.x)]) == gen, bar);
.LBB0_742:
	v_readlane_b32 s2, v254, 32
	v_readlane_b32 s3, v254, 33
	s_waitcnt vmcnt(0) expcnt(0) lgkmcnt(0)
	s_add_i32 s21, s23, 2
	v_mov_b64_e32 v[0:1], s[2:3]
	flat_atomic_add v0, v[0:1], v174 sc0
	v_readlane_b32 s2, v255, 32
	s_mul_i32 s2, s21, s2
	s_waitcnt vmcnt(0) lgkmcnt(0)
	v_add_u32_e32 v0, 1, v0
	v_cmp_ne_u32_e32 vcc, s2, v0
	s_and_saveexec_b64 s[2:3], vcc
	s_xor_b64 s[2:3], exec, s[2:3]
	s_cbranch_execz .LBB0_755
	v_readlane_b32 s4, v254, 40
	v_readlane_b32 s5, v254, 41
	s_nop 1
	v_mov_b64_e32 v[0:1], s[4:5]
	flat_load_dword v0, v[0:1] sc1
	s_waitcnt vmcnt(0) lgkmcnt(0)
	v_cmp_eq_u32_e32 vcc, s20, v0
	s_and_saveexec_b64 s[4:5], vcc
	s_cbranch_execz .LBB0_754
	s_mov_b32 s22, 1
	s_mov_b64 s[6:7], 0
	s_branch .LBB0_746
